# gated projection epilogue made rolling: each step re-issues its gate/merged quads for the next 4-step batch, only the first batch's latency is exposed
# baseline (speedup 1.0000x reference)
; DI float bf_lo(unsigned u) { return __uint_as_float(u << 16); }
; DI float bf_hi(unsigned u) { return __uint_as_float(u & 0xffff0000u); }
; #define EPI_ROWS for (int ai = 0; ai < 2; ++ai) for (int m = 0; m < 4; ++m, ({ asm volatile("" ::: "memory"); }))
; DI void store_bf8(bf16_t* p, f32x4 a, f32x4 b) { u32x4 w; w.x = pk2(a[0], a[1]); w.y = pk2(a[2], a[3]); w.z = pk2(b[0], b[1]); w.w = pk2(b[2], b[3]); *(u32x4*)p = w; }
; DI void gemm_run(const GemmDesc& d, char* lds) {
;     ...
;         case E_PROJA: case E_PROJB: {
;             const int goff = d.epi == E_PROJA ? 0 : 1024, c8 = bcol + wc * 32 + fq * 8;
; #pragma unroll
;             EPI_ROWS { const int row = rbase + ai * 128 + m * 16;
; #pragma unroll
;                 for (int bj = 0; bj < 2; ++bj) { const int c = c8 + bj * 128; const u32x4 gw = *(const u32x4*)(P->gates + (long)row * 2048 + goff + c);
;                     f32x4 g0 = {bf_lo(gw.x), bf_hi(gw.x), bf_lo(gw.y), bf_hi(gw.y)}, g1 = {bf_lo(gw.z), bf_hi(gw.z), bf_lo(gw.w), bf_hi(gw.w)};
;                     f32x4 v0 = acc[ai][bj][m][0] * g0, v1 = acc[ai][bj][m][1] * g1;
;                     bf16_t* dst = P->merged + (long)row * 1024 + c;
;                     if (d.epi == E_PROJB) { const u32x4 pw = *(const u32x4*)dst;
;                         v0 += (f32x4){bf_lo(pw.x), bf_hi(pw.x), bf_lo(pw.y), bf_hi(pw.y)}; v1 += (f32x4){bf_lo(pw.z), bf_hi(pw.z), bf_lo(pw.w), bf_hi(pw.w)}; }
;                     store_bf8(dst, v0, v1); } }
;         } break;
.LBB0_613:
	s_andn2_b64 vcc, exec, s[2:3]
	s_cbranch_vccnz .LBB0_778
	s_cmp_lg_u32 s65, 3
	s_mov_b64 s[2:3], -1
	s_cbranch_scc0 .LBB0_648
	s_load_dwordx4 s[8:11], s[58:59], 0x168
	v_lshl_add_u32 v128, v206, 3, s63
	v_lshlrev_b32_e32 v128, 1, v128
	v_lshl_add_u32 v130, v146, 12, v128
	v_lshl_add_u32 v131, v146, 11, v128
	s_waitcnt lgkmcnt(0)
	s_add_u32 s2, s8, s20
	s_addc_u32 s3, s9, 0
	s_andn2_b64 vcc, exec, s[52:53]
	s_cbranch_vccnz .Lproj_a
	v_mov_b32_e32 v128, v130
	global_load_dwordx4 v[208:211], v128, s[2:3]
	v_mov_b32_e32 v129, v131
	global_load_dwordx4 v[224:227], v129, s[10:11]
	v_mov_b32_e32 v128, v130
	global_load_dwordx4 v[212:215], v128, s[2:3] offset:256
	v_mov_b32_e32 v129, v131
	global_load_dwordx4 v[228:231], v129, s[10:11] offset:256
	v_add_u32_e32 v128, 0x10000, v130
	global_load_dwordx4 v[216:219], v128, s[2:3]
	v_add_u32_e32 v129, 0x8000, v131
	global_load_dwordx4 v[232:235], v129, s[10:11]
	v_add_u32_e32 v128, 0x10000, v130
	global_load_dwordx4 v[220:223], v128, s[2:3] offset:256
	v_add_u32_e32 v129, 0x8000, v131
	global_load_dwordx4 v[236:239], v129, s[10:11] offset:256
	s_waitcnt vmcnt(6)
	v_lshlrev_b32_e32 v240, 16, v208
	v_and_b32_e32 v241, 0xffff0000, v208
	v_lshlrev_b32_e32 v242, 16, v209
	v_and_b32_e32 v243, 0xffff0000, v209
	v_lshlrev_b32_e32 v244, 16, v210
	v_and_b32_e32 v245, 0xffff0000, v210
	v_lshlrev_b32_e32 v246, 16, v211
	v_and_b32_e32 v247, 0xffff0000, v211
	v_lshlrev_b32_e32 v150, 16, v224
	v_and_b32_e32 v151, 0xffff0000, v224
	v_lshlrev_b32_e32 v152, 16, v225
	v_and_b32_e32 v153, 0xffff0000, v225
	v_lshlrev_b32_e32 v154, 16, v226
	v_and_b32_e32 v155, 0xffff0000, v226
	v_lshlrev_b32_e32 v156, 16, v227
	v_and_b32_e32 v157, 0xffff0000, v227
	v_mul_f32_e32 v240, v124, v240
	v_mul_f32_e32 v241, v125, v241
	v_mul_f32_e32 v242, v126, v242
	v_mul_f32_e32 v243, v127, v243
	v_mul_f32_e32 v244, v120, v244
	v_mul_f32_e32 v245, v121, v245
	v_mul_f32_e32 v246, v122, v246
	v_mul_f32_e32 v247, v123, v247
	v_add_f32_e32 v240, v240, v150
	v_add_f32_e32 v241, v241, v151
	v_add_f32_e32 v242, v242, v152
	v_add_f32_e32 v243, v243, v153
	v_add_f32_e32 v244, v244, v154
	v_add_f32_e32 v245, v245, v155
	v_add_f32_e32 v246, v246, v156
	v_add_f32_e32 v247, v247, v157
	v_cvt_pk_bf16_f32 v158, v240, v241
	v_cvt_pk_bf16_f32 v159, v242, v243
	v_cvt_pk_bf16_f32 v160, v244, v245
	v_cvt_pk_bf16_f32 v161, v246, v247
	v_mov_b32_e32 v129, v131
	global_store_dwordx4 v129, v[158:161], s[10:11]
	v_add_u32_e32 v128, 0x20000, v130
	global_load_dwordx4 v[208:211], v128, s[2:3]
	v_add_u32_e32 v129, 0x10000, v131
	global_load_dwordx4 v[224:227], v129, s[10:11]
	s_waitcnt vmcnt(7)
	v_lshlrev_b32_e32 v240, 16, v212
	v_and_b32_e32 v241, 0xffff0000, v212
	v_lshlrev_b32_e32 v242, 16, v213
	v_and_b32_e32 v243, 0xffff0000, v213
	v_lshlrev_b32_e32 v244, 16, v214
	v_and_b32_e32 v245, 0xffff0000, v214
	v_lshlrev_b32_e32 v246, 16, v215
	v_and_b32_e32 v247, 0xffff0000, v215
	v_lshlrev_b32_e32 v150, 16, v228
	v_and_b32_e32 v151, 0xffff0000, v228
	v_lshlrev_b32_e32 v152, 16, v229
	v_and_b32_e32 v153, 0xffff0000, v229
	v_lshlrev_b32_e32 v154, 16, v230
	v_and_b32_e32 v155, 0xffff0000, v230
	v_lshlrev_b32_e32 v156, 16, v231
	v_and_b32_e32 v157, 0xffff0000, v231
	v_mul_f32_e32 v240, v108, v240
	v_mul_f32_e32 v241, v109, v241
	v_mul_f32_e32 v242, v110, v242
	v_mul_f32_e32 v243, v111, v243
	v_mul_f32_e32 v244, v104, v244
	v_mul_f32_e32 v245, v105, v245
	v_mul_f32_e32 v246, v106, v246
	v_mul_f32_e32 v247, v107, v247
	v_add_f32_e32 v240, v240, v150
	v_add_f32_e32 v241, v241, v151
	v_add_f32_e32 v242, v242, v152
	v_add_f32_e32 v243, v243, v153
	v_add_f32_e32 v244, v244, v154
	v_add_f32_e32 v245, v245, v155
	v_add_f32_e32 v246, v246, v156
	v_add_f32_e32 v247, v247, v157
	v_cvt_pk_bf16_f32 v166, v240, v241
	v_cvt_pk_bf16_f32 v167, v242, v243
	v_cvt_pk_bf16_f32 v168, v244, v245
	v_cvt_pk_bf16_f32 v169, v246, v247
	v_mov_b32_e32 v129, v131
	global_store_dwordx4 v129, v[166:169], s[10:11] offset:256
	v_add_u32_e32 v128, 0x20000, v130
	global_load_dwordx4 v[212:215], v128, s[2:3] offset:256
	v_add_u32_e32 v129, 0x10000, v131
	global_load_dwordx4 v[228:231], v129, s[10:11] offset:256
	s_waitcnt vmcnt(8)
	v_lshlrev_b32_e32 v240, 16, v216
	v_and_b32_e32 v241, 0xffff0000, v216
	v_lshlrev_b32_e32 v242, 16, v217
	v_and_b32_e32 v243, 0xffff0000, v217
	v_lshlrev_b32_e32 v244, 16, v218
	v_and_b32_e32 v245, 0xffff0000, v218
	v_lshlrev_b32_e32 v246, 16, v219
	v_and_b32_e32 v247, 0xffff0000, v219
	v_lshlrev_b32_e32 v150, 16, v232
	v_and_b32_e32 v151, 0xffff0000, v232
	v_lshlrev_b32_e32 v152, 16, v233
	v_and_b32_e32 v153, 0xffff0000, v233
	v_lshlrev_b32_e32 v154, 16, v234
	v_and_b32_e32 v155, 0xffff0000, v234
	v_lshlrev_b32_e32 v156, 16, v235
	v_and_b32_e32 v157, 0xffff0000, v235
	v_mul_f32_e32 v240, v116, v240
	v_mul_f32_e32 v241, v117, v241
	v_mul_f32_e32 v242, v118, v242
	v_mul_f32_e32 v243, v119, v243
	v_mul_f32_e32 v244, v112, v244
	v_mul_f32_e32 v245, v113, v245
	v_mul_f32_e32 v246, v114, v246
	v_mul_f32_e32 v247, v115, v247
	v_add_f32_e32 v240, v240, v150
	v_add_f32_e32 v241, v241, v151
	v_add_f32_e32 v242, v242, v152
	v_add_f32_e32 v243, v243, v153
	v_add_f32_e32 v244, v244, v154
	v_add_f32_e32 v245, v245, v155
	v_add_f32_e32 v246, v246, v156
	v_add_f32_e32 v247, v247, v157
	v_cvt_pk_bf16_f32 v158, v240, v241
	v_cvt_pk_bf16_f32 v159, v242, v243
	v_cvt_pk_bf16_f32 v160, v244, v245
	v_cvt_pk_bf16_f32 v161, v246, v247
	v_add_u32_e32 v129, 0x8000, v131
	global_store_dwordx4 v129, v[158:161], s[10:11]
	v_add_u32_e32 v128, 0x30000, v130
	global_load_dwordx4 v[216:219], v128, s[2:3]
	v_add_u32_e32 v129, 0x18000, v131
	global_load_dwordx4 v[232:235], v129, s[10:11]
	s_waitcnt vmcnt(9)
; DI float bf_lo(unsigned u) { return __uint_as_float(u << 16); }
; DI float bf_hi(unsigned u) { return __uint_as_float(u & 0xffff0000u); }
; #define EPI_ROWS for (int ai = 0; ai < 2; ++ai) for (int m = 0; m < 4; ++m, ({ asm volatile("" ::: "memory"); }))
; DI void store_bf8(bf16_t* p, f32x4 a, f32x4 b) { u32x4 w; w.x = pk2(a[0], a[1]); w.y = pk2(a[2], a[3]); w.z = pk2(b[0], b[1]); w.w = pk2(b[2], b[3]); *(u32x4*)p = w; }
; DI void gemm_run(const GemmDesc& d, char* lds) {
;     ...
;         case E_PROJA: case E_PROJB: {
;             const int goff = d.epi == E_PROJA ? 0 : 1024, c8 = bcol + wc * 32 + fq * 8;
; #pragma unroll
;             EPI_ROWS { const int row = rbase + ai * 128 + m * 16;
; #pragma unroll
;                 for (int bj = 0; bj < 2; ++bj) { const int c = c8 + bj * 128; const u32x4 gw = *(const u32x4*)(P->gates + (long)row * 2048 + goff + c);
;                     f32x4 g0 = {bf_lo(gw.x), bf_hi(gw.x), bf_lo(gw.y), bf_hi(gw.y)}, g1 = {bf_lo(gw.z), bf_hi(gw.z), bf_lo(gw.w), bf_hi(gw.w)};
;                     f32x4 v0 = acc[ai][bj][m][0] * g0, v1 = acc[ai][bj][m][1] * g1;
;                     bf16_t* dst = P->merged + (long)row * 1024 + c;
;                     if (d.epi == E_PROJB) { const u32x4 pw = *(const u32x4*)dst;
;                         v0 += (f32x4){bf_lo(pw.x), bf_hi(pw.x), bf_lo(pw.y), bf_hi(pw.y)}; v1 += (f32x4){bf_lo(pw.z), bf_hi(pw.z), bf_lo(pw.w), bf_hi(pw.w)}; }
;                     store_bf8(dst, v0, v1); } }
;         } break;
	v_lshlrev_b32_e32 v240, 16, v220
	v_and_b32_e32 v241, 0xffff0000, v220
	v_lshlrev_b32_e32 v242, 16, v221
	v_and_b32_e32 v243, 0xffff0000, v221
	v_lshlrev_b32_e32 v244, 16, v222
	v_and_b32_e32 v245, 0xffff0000, v222
	v_lshlrev_b32_e32 v246, 16, v223
	v_and_b32_e32 v247, 0xffff0000, v223
	v_lshlrev_b32_e32 v150, 16, v236
	v_and_b32_e32 v151, 0xffff0000, v236
	v_lshlrev_b32_e32 v152, 16, v237
	v_and_b32_e32 v153, 0xffff0000, v237
	v_lshlrev_b32_e32 v154, 16, v238
	v_and_b32_e32 v155, 0xffff0000, v238
	v_lshlrev_b32_e32 v156, 16, v239
	v_and_b32_e32 v157, 0xffff0000, v239
	v_mul_f32_e32 v240, v92, v240
	v_mul_f32_e32 v241, v93, v241
	v_mul_f32_e32 v242, v94, v242
	v_mul_f32_e32 v243, v95, v243
	v_mul_f32_e32 v244, v88, v244
	v_mul_f32_e32 v245, v89, v245
	v_mul_f32_e32 v246, v90, v246
	v_mul_f32_e32 v247, v91, v247
	v_add_f32_e32 v240, v240, v150
	v_add_f32_e32 v241, v241, v151
	v_add_f32_e32 v242, v242, v152
	v_add_f32_e32 v243, v243, v153
	v_add_f32_e32 v244, v244, v154
	v_add_f32_e32 v245, v245, v155
	v_add_f32_e32 v246, v246, v156
	v_add_f32_e32 v247, v247, v157
	v_cvt_pk_bf16_f32 v166, v240, v241
	v_cvt_pk_bf16_f32 v167, v242, v243
	v_cvt_pk_bf16_f32 v168, v244, v245
	v_cvt_pk_bf16_f32 v169, v246, v247
	v_add_u32_e32 v129, 0x8000, v131
	global_store_dwordx4 v129, v[166:169], s[10:11] offset:256
	v_add_u32_e32 v128, 0x30000, v130
	global_load_dwordx4 v[220:223], v128, s[2:3] offset:256
	v_add_u32_e32 v129, 0x18000, v131
	global_load_dwordx4 v[236:239], v129, s[10:11] offset:256
	s_waitcnt vmcnt(9)
	v_lshlrev_b32_e32 v240, 16, v208
	v_and_b32_e32 v241, 0xffff0000, v208
	v_lshlrev_b32_e32 v242, 16, v209
	v_and_b32_e32 v243, 0xffff0000, v209
	v_lshlrev_b32_e32 v244, 16, v210
	v_and_b32_e32 v245, 0xffff0000, v210
	v_lshlrev_b32_e32 v246, 16, v211
	v_and_b32_e32 v247, 0xffff0000, v211
	v_lshlrev_b32_e32 v150, 16, v224
	v_and_b32_e32 v151, 0xffff0000, v224
	v_lshlrev_b32_e32 v152, 16, v225
	v_and_b32_e32 v153, 0xffff0000, v225
	v_lshlrev_b32_e32 v154, 16, v226
	v_and_b32_e32 v155, 0xffff0000, v226
	v_lshlrev_b32_e32 v156, 16, v227
	v_and_b32_e32 v157, 0xffff0000, v227
	v_mul_f32_e32 v240, v100, v240
	v_mul_f32_e32 v241, v101, v241
	v_mul_f32_e32 v242, v102, v242
	v_mul_f32_e32 v243, v103, v243
	v_mul_f32_e32 v244, v96, v244
	v_mul_f32_e32 v245, v97, v245
	v_mul_f32_e32 v246, v98, v246
	v_mul_f32_e32 v247, v99, v247
	v_add_f32_e32 v240, v240, v150
	v_add_f32_e32 v241, v241, v151
	v_add_f32_e32 v242, v242, v152
	v_add_f32_e32 v243, v243, v153
	v_add_f32_e32 v244, v244, v154
	v_add_f32_e32 v245, v245, v155
	v_add_f32_e32 v246, v246, v156
	v_add_f32_e32 v247, v247, v157
	v_cvt_pk_bf16_f32 v158, v240, v241
	v_cvt_pk_bf16_f32 v159, v242, v243
	v_cvt_pk_bf16_f32 v160, v244, v245
	v_cvt_pk_bf16_f32 v161, v246, v247
	v_add_u32_e32 v129, 0x10000, v131
	global_store_dwordx4 v129, v[158:161], s[10:11]
	v_add_u32_e32 v128, 0x80000, v130
	global_load_dwordx4 v[208:211], v128, s[2:3]
	v_add_u32_e32 v129, 0x40000, v131
	global_load_dwordx4 v[224:227], v129, s[10:11]
	s_waitcnt vmcnt(9)
	v_lshlrev_b32_e32 v240, 16, v212
	v_and_b32_e32 v241, 0xffff0000, v212
	v_lshlrev_b32_e32 v242, 16, v213
	v_and_b32_e32 v243, 0xffff0000, v213
	v_lshlrev_b32_e32 v244, 16, v214
	v_and_b32_e32 v245, 0xffff0000, v214
	v_lshlrev_b32_e32 v246, 16, v215
	v_and_b32_e32 v247, 0xffff0000, v215
	v_lshlrev_b32_e32 v150, 16, v228
	v_and_b32_e32 v151, 0xffff0000, v228
	v_lshlrev_b32_e32 v152, 16, v229
	v_and_b32_e32 v153, 0xffff0000, v229
	v_lshlrev_b32_e32 v154, 16, v230
	v_and_b32_e32 v155, 0xffff0000, v230
	v_lshlrev_b32_e32 v156, 16, v231
	v_and_b32_e32 v157, 0xffff0000, v231
	v_mul_f32_e32 v240, v76, v240
	v_mul_f32_e32 v241, v77, v241
	v_mul_f32_e32 v242, v78, v242
	v_mul_f32_e32 v243, v79, v243
	v_mul_f32_e32 v244, v72, v244
	v_mul_f32_e32 v245, v73, v245
	v_mul_f32_e32 v246, v74, v246
	v_mul_f32_e32 v247, v75, v247
	v_add_f32_e32 v240, v240, v150
	v_add_f32_e32 v241, v241, v151
	v_add_f32_e32 v242, v242, v152
	v_add_f32_e32 v243, v243, v153
	v_add_f32_e32 v244, v244, v154
	v_add_f32_e32 v245, v245, v155
	v_add_f32_e32 v246, v246, v156
	v_add_f32_e32 v247, v247, v157
	v_cvt_pk_bf16_f32 v166, v240, v241
	v_cvt_pk_bf16_f32 v167, v242, v243
	v_cvt_pk_bf16_f32 v168, v244, v245
	v_cvt_pk_bf16_f32 v169, v246, v247
	v_add_u32_e32 v129, 0x10000, v131
	global_store_dwordx4 v129, v[166:169], s[10:11] offset:256
	v_add_u32_e32 v128, 0x80000, v130
	global_load_dwordx4 v[212:215], v128, s[2:3] offset:256
	v_add_u32_e32 v129, 0x40000, v131
	global_load_dwordx4 v[228:231], v129, s[10:11] offset:256
	s_waitcnt vmcnt(9)
	v_lshlrev_b32_e32 v240, 16, v216
	v_and_b32_e32 v241, 0xffff0000, v216
	v_lshlrev_b32_e32 v242, 16, v217
	v_and_b32_e32 v243, 0xffff0000, v217
	v_lshlrev_b32_e32 v244, 16, v218
	v_and_b32_e32 v245, 0xffff0000, v218
	v_lshlrev_b32_e32 v246, 16, v219
	v_and_b32_e32 v247, 0xffff0000, v219
	v_lshlrev_b32_e32 v150, 16, v232
	v_and_b32_e32 v151, 0xffff0000, v232
	v_lshlrev_b32_e32 v152, 16, v233
	v_and_b32_e32 v153, 0xffff0000, v233
	v_lshlrev_b32_e32 v154, 16, v234
	v_and_b32_e32 v155, 0xffff0000, v234
	v_lshlrev_b32_e32 v156, 16, v235
	v_and_b32_e32 v157, 0xffff0000, v235
	v_mul_f32_e32 v240, v84, v240
	v_mul_f32_e32 v241, v85, v241
	v_mul_f32_e32 v242, v86, v242
	v_mul_f32_e32 v243, v87, v243
	v_mul_f32_e32 v244, v80, v244
	v_mul_f32_e32 v245, v81, v245
	v_mul_f32_e32 v246, v82, v246
	v_mul_f32_e32 v247, v83, v247
	v_add_f32_e32 v240, v240, v150
	v_add_f32_e32 v241, v241, v151
	v_add_f32_e32 v242, v242, v152
	v_add_f32_e32 v243, v243, v153
	v_add_f32_e32 v244, v244, v154
	v_add_f32_e32 v245, v245, v155
	v_add_f32_e32 v246, v246, v156
	v_add_f32_e32 v247, v247, v157
	v_cvt_pk_bf16_f32 v158, v240, v241
	v_cvt_pk_bf16_f32 v159, v242, v243
	v_cvt_pk_bf16_f32 v160, v244, v245
	v_cvt_pk_bf16_f32 v161, v246, v247
	v_add_u32_e32 v129, 0x18000, v131
	global_store_dwordx4 v129, v[158:161], s[10:11]
	v_add_u32_e32 v128, 0x90000, v130
	global_load_dwordx4 v[216:219], v128, s[2:3]
	v_add_u32_e32 v129, 0x48000, v131
	global_load_dwordx4 v[232:235], v129, s[10:11]
	s_waitcnt vmcnt(9)
; DI float bf_lo(unsigned u) { return __uint_as_float(u << 16); }
; DI float bf_hi(unsigned u) { return __uint_as_float(u & 0xffff0000u); }
; #define EPI_ROWS for (int ai = 0; ai < 2; ++ai) for (int m = 0; m < 4; ++m, ({ asm volatile("" ::: "memory"); }))
; DI void store_bf8(bf16_t* p, f32x4 a, f32x4 b) { u32x4 w; w.x = pk2(a[0], a[1]); w.y = pk2(a[2], a[3]); w.z = pk2(b[0], b[1]); w.w = pk2(b[2], b[3]); *(u32x4*)p = w; }
; DI void gemm_run(const GemmDesc& d, char* lds) {
;     ...
;         case E_PROJA: case E_PROJB: {
;             const int goff = d.epi == E_PROJA ? 0 : 1024, c8 = bcol + wc * 32 + fq * 8;
; #pragma unroll
;             EPI_ROWS { const int row = rbase + ai * 128 + m * 16;
; #pragma unroll
;                 for (int bj = 0; bj < 2; ++bj) { const int c = c8 + bj * 128; const u32x4 gw = *(const u32x4*)(P->gates + (long)row * 2048 + goff + c);
;                     f32x4 g0 = {bf_lo(gw.x), bf_hi(gw.x), bf_lo(gw.y), bf_hi(gw.y)}, g1 = {bf_lo(gw.z), bf_hi(gw.z), bf_lo(gw.w), bf_hi(gw.w)};
;                     f32x4 v0 = acc[ai][bj][m][0] * g0, v1 = acc[ai][bj][m][1] * g1;
;                     bf16_t* dst = P->merged + (long)row * 1024 + c;
;                     if (d.epi == E_PROJB) { const u32x4 pw = *(const u32x4*)dst;
;                         v0 += (f32x4){bf_lo(pw.x), bf_hi(pw.x), bf_lo(pw.y), bf_hi(pw.y)}; v1 += (f32x4){bf_lo(pw.z), bf_hi(pw.z), bf_lo(pw.w), bf_hi(pw.w)}; }
;                     store_bf8(dst, v0, v1); } }
;         } break;
	v_lshlrev_b32_e32 v240, 16, v220
	v_and_b32_e32 v241, 0xffff0000, v220
	v_lshlrev_b32_e32 v242, 16, v221
	v_and_b32_e32 v243, 0xffff0000, v221
	v_lshlrev_b32_e32 v244, 16, v222
	v_and_b32_e32 v245, 0xffff0000, v222
	v_lshlrev_b32_e32 v246, 16, v223
	v_and_b32_e32 v247, 0xffff0000, v223
	v_lshlrev_b32_e32 v150, 16, v236
	v_and_b32_e32 v151, 0xffff0000, v236
	v_lshlrev_b32_e32 v152, 16, v237
	v_and_b32_e32 v153, 0xffff0000, v237
	v_lshlrev_b32_e32 v154, 16, v238
	v_and_b32_e32 v155, 0xffff0000, v238
	v_lshlrev_b32_e32 v156, 16, v239
	v_and_b32_e32 v157, 0xffff0000, v239
	v_mul_f32_e32 v240, v68, v240
	v_mul_f32_e32 v241, v69, v241
	v_mul_f32_e32 v242, v70, v242
	v_mul_f32_e32 v243, v71, v243
	v_mul_f32_e32 v244, v64, v244
	v_mul_f32_e32 v245, v65, v245
	v_mul_f32_e32 v246, v66, v246
	v_mul_f32_e32 v247, v67, v247
	v_add_f32_e32 v240, v240, v150
	v_add_f32_e32 v241, v241, v151
	v_add_f32_e32 v242, v242, v152
	v_add_f32_e32 v243, v243, v153
	v_add_f32_e32 v244, v244, v154
	v_add_f32_e32 v245, v245, v155
	v_add_f32_e32 v246, v246, v156
	v_add_f32_e32 v247, v247, v157
	v_cvt_pk_bf16_f32 v166, v240, v241
	v_cvt_pk_bf16_f32 v167, v242, v243
	v_cvt_pk_bf16_f32 v168, v244, v245
	v_cvt_pk_bf16_f32 v169, v246, v247
	v_add_u32_e32 v129, 0x18000, v131
	global_store_dwordx4 v129, v[166:169], s[10:11] offset:256
	v_add_u32_e32 v128, 0x90000, v130
	global_load_dwordx4 v[220:223], v128, s[2:3] offset:256
	v_add_u32_e32 v129, 0x48000, v131
	global_load_dwordx4 v[236:239], v129, s[10:11] offset:256
	s_waitcnt vmcnt(9)
	v_lshlrev_b32_e32 v240, 16, v208
	v_and_b32_e32 v241, 0xffff0000, v208
	v_lshlrev_b32_e32 v242, 16, v209
	v_and_b32_e32 v243, 0xffff0000, v209
	v_lshlrev_b32_e32 v244, 16, v210
	v_and_b32_e32 v245, 0xffff0000, v210
	v_lshlrev_b32_e32 v246, 16, v211
	v_and_b32_e32 v247, 0xffff0000, v211
	v_lshlrev_b32_e32 v150, 16, v224
	v_and_b32_e32 v151, 0xffff0000, v224
	v_lshlrev_b32_e32 v152, 16, v225
	v_and_b32_e32 v153, 0xffff0000, v225
	v_lshlrev_b32_e32 v154, 16, v226
	v_and_b32_e32 v155, 0xffff0000, v226
	v_lshlrev_b32_e32 v156, 16, v227
	v_and_b32_e32 v157, 0xffff0000, v227
	v_mul_f32_e32 v240, v60, v240
	v_mul_f32_e32 v241, v61, v241
	v_mul_f32_e32 v242, v62, v242
	v_mul_f32_e32 v243, v63, v243
	v_mul_f32_e32 v244, v56, v244
	v_mul_f32_e32 v245, v57, v245
	v_mul_f32_e32 v246, v58, v246
	v_mul_f32_e32 v247, v59, v247
	v_add_f32_e32 v240, v240, v150
	v_add_f32_e32 v241, v241, v151
	v_add_f32_e32 v242, v242, v152
	v_add_f32_e32 v243, v243, v153
	v_add_f32_e32 v244, v244, v154
	v_add_f32_e32 v245, v245, v155
	v_add_f32_e32 v246, v246, v156
	v_add_f32_e32 v247, v247, v157
	v_cvt_pk_bf16_f32 v158, v240, v241
	v_cvt_pk_bf16_f32 v159, v242, v243
	v_cvt_pk_bf16_f32 v160, v244, v245
	v_cvt_pk_bf16_f32 v161, v246, v247
	v_add_u32_e32 v129, 0x40000, v131
	global_store_dwordx4 v129, v[158:161], s[10:11]
	v_add_u32_e32 v128, 0xa0000, v130
	global_load_dwordx4 v[208:211], v128, s[2:3]
	v_add_u32_e32 v129, 0x50000, v131
	global_load_dwordx4 v[224:227], v129, s[10:11]
	s_waitcnt vmcnt(9)
	v_lshlrev_b32_e32 v240, 16, v212
	v_and_b32_e32 v241, 0xffff0000, v212
	v_lshlrev_b32_e32 v242, 16, v213
	v_and_b32_e32 v243, 0xffff0000, v213
	v_lshlrev_b32_e32 v244, 16, v214
	v_and_b32_e32 v245, 0xffff0000, v214
	v_lshlrev_b32_e32 v246, 16, v215
	v_and_b32_e32 v247, 0xffff0000, v215
	v_lshlrev_b32_e32 v150, 16, v228
	v_and_b32_e32 v151, 0xffff0000, v228
	v_lshlrev_b32_e32 v152, 16, v229
	v_and_b32_e32 v153, 0xffff0000, v229
	v_lshlrev_b32_e32 v154, 16, v230
	v_and_b32_e32 v155, 0xffff0000, v230
	v_lshlrev_b32_e32 v156, 16, v231
	v_and_b32_e32 v157, 0xffff0000, v231
	v_mul_f32_e32 v240, v44, v240
	v_mul_f32_e32 v241, v45, v241
	v_mul_f32_e32 v242, v46, v242
	v_mul_f32_e32 v243, v47, v243
	v_mul_f32_e32 v244, v40, v244
	v_mul_f32_e32 v245, v41, v245
	v_mul_f32_e32 v246, v42, v246
	v_mul_f32_e32 v247, v43, v247
	v_add_f32_e32 v240, v240, v150
	v_add_f32_e32 v241, v241, v151
	v_add_f32_e32 v242, v242, v152
	v_add_f32_e32 v243, v243, v153
	v_add_f32_e32 v244, v244, v154
	v_add_f32_e32 v245, v245, v155
	v_add_f32_e32 v246, v246, v156
	v_add_f32_e32 v247, v247, v157
	v_cvt_pk_bf16_f32 v166, v240, v241
	v_cvt_pk_bf16_f32 v167, v242, v243
	v_cvt_pk_bf16_f32 v168, v244, v245
	v_cvt_pk_bf16_f32 v169, v246, v247
	v_add_u32_e32 v129, 0x40000, v131
	global_store_dwordx4 v129, v[166:169], s[10:11] offset:256
	v_add_u32_e32 v128, 0xa0000, v130
	global_load_dwordx4 v[212:215], v128, s[2:3] offset:256
	v_add_u32_e32 v129, 0x50000, v131
	global_load_dwordx4 v[228:231], v129, s[10:11] offset:256
	s_waitcnt vmcnt(9)
	v_lshlrev_b32_e32 v240, 16, v216
	v_and_b32_e32 v241, 0xffff0000, v216
	v_lshlrev_b32_e32 v242, 16, v217
	v_and_b32_e32 v243, 0xffff0000, v217
	v_lshlrev_b32_e32 v244, 16, v218
	v_and_b32_e32 v245, 0xffff0000, v218
	v_lshlrev_b32_e32 v246, 16, v219
	v_and_b32_e32 v247, 0xffff0000, v219
	v_lshlrev_b32_e32 v150, 16, v232
	v_and_b32_e32 v151, 0xffff0000, v232
	v_lshlrev_b32_e32 v152, 16, v233
	v_and_b32_e32 v153, 0xffff0000, v233
	v_lshlrev_b32_e32 v154, 16, v234
	v_and_b32_e32 v155, 0xffff0000, v234
	v_lshlrev_b32_e32 v156, 16, v235
	v_and_b32_e32 v157, 0xffff0000, v235
	v_mul_f32_e32 v240, v52, v240
	v_mul_f32_e32 v241, v53, v241
	v_mul_f32_e32 v242, v54, v242
	v_mul_f32_e32 v243, v55, v243
	v_mul_f32_e32 v244, v48, v244
	v_mul_f32_e32 v245, v49, v245
	v_mul_f32_e32 v246, v50, v246
	v_mul_f32_e32 v247, v51, v247
	v_add_f32_e32 v240, v240, v150
	v_add_f32_e32 v241, v241, v151
	v_add_f32_e32 v242, v242, v152
	v_add_f32_e32 v243, v243, v153
	v_add_f32_e32 v244, v244, v154
	v_add_f32_e32 v245, v245, v155
	v_add_f32_e32 v246, v246, v156
	v_add_f32_e32 v247, v247, v157
	v_cvt_pk_bf16_f32 v158, v240, v241
	v_cvt_pk_bf16_f32 v159, v242, v243
	v_cvt_pk_bf16_f32 v160, v244, v245
	v_cvt_pk_bf16_f32 v161, v246, v247
	v_add_u32_e32 v129, 0x48000, v131
	global_store_dwordx4 v129, v[158:161], s[10:11]
	v_add_u32_e32 v128, 0xb0000, v130
	global_load_dwordx4 v[216:219], v128, s[2:3]
	v_add_u32_e32 v129, 0x58000, v131
	global_load_dwordx4 v[232:235], v129, s[10:11]
	s_waitcnt vmcnt(9)
; DI float bf_lo(unsigned u) { return __uint_as_float(u << 16); }
; DI float bf_hi(unsigned u) { return __uint_as_float(u & 0xffff0000u); }
; #define EPI_ROWS for (int ai = 0; ai < 2; ++ai) for (int m = 0; m < 4; ++m, ({ asm volatile("" ::: "memory"); }))
; DI void store_bf8(bf16_t* p, f32x4 a, f32x4 b) { u32x4 w; w.x = pk2(a[0], a[1]); w.y = pk2(a[2], a[3]); w.z = pk2(b[0], b[1]); w.w = pk2(b[2], b[3]); *(u32x4*)p = w; }
; DI void gemm_run(const GemmDesc& d, char* lds) {
;     ...
;         case E_PROJA: case E_PROJB: {
;             const int goff = d.epi == E_PROJA ? 0 : 1024, c8 = bcol + wc * 32 + fq * 8;
; #pragma unroll
;             EPI_ROWS { const int row = rbase + ai * 128 + m * 16;
; #pragma unroll
;                 for (int bj = 0; bj < 2; ++bj) { const int c = c8 + bj * 128; const u32x4 gw = *(const u32x4*)(P->gates + (long)row * 2048 + goff + c);
;                     f32x4 g0 = {bf_lo(gw.x), bf_hi(gw.x), bf_lo(gw.y), bf_hi(gw.y)}, g1 = {bf_lo(gw.z), bf_hi(gw.z), bf_lo(gw.w), bf_hi(gw.w)};
;                     f32x4 v0 = acc[ai][bj][m][0] * g0, v1 = acc[ai][bj][m][1] * g1;
;                     bf16_t* dst = P->merged + (long)row * 1024 + c;
;                     if (d.epi == E_PROJB) { const u32x4 pw = *(const u32x4*)dst;
;                         v0 += (f32x4){bf_lo(pw.x), bf_hi(pw.x), bf_lo(pw.y), bf_hi(pw.y)}; v1 += (f32x4){bf_lo(pw.z), bf_hi(pw.z), bf_lo(pw.w), bf_hi(pw.w)}; }
;                     store_bf8(dst, v0, v1); } }
;         } break;
	v_lshlrev_b32_e32 v240, 16, v220
	v_and_b32_e32 v241, 0xffff0000, v220
	v_lshlrev_b32_e32 v242, 16, v221
	v_and_b32_e32 v243, 0xffff0000, v221
	v_lshlrev_b32_e32 v244, 16, v222
	v_and_b32_e32 v245, 0xffff0000, v222
	v_lshlrev_b32_e32 v246, 16, v223
	v_and_b32_e32 v247, 0xffff0000, v223
	v_lshlrev_b32_e32 v150, 16, v236
	v_and_b32_e32 v151, 0xffff0000, v236
	v_lshlrev_b32_e32 v152, 16, v237
	v_and_b32_e32 v153, 0xffff0000, v237
	v_lshlrev_b32_e32 v154, 16, v238
	v_and_b32_e32 v155, 0xffff0000, v238
	v_lshlrev_b32_e32 v156, 16, v239
	v_and_b32_e32 v157, 0xffff0000, v239
	v_mul_f32_e32 v240, v28, v240
	v_mul_f32_e32 v241, v29, v241
	v_mul_f32_e32 v242, v30, v242
	v_mul_f32_e32 v243, v31, v243
	v_mul_f32_e32 v244, v24, v244
	v_mul_f32_e32 v245, v25, v245
	v_mul_f32_e32 v246, v26, v246
	v_mul_f32_e32 v247, v27, v247
	v_add_f32_e32 v240, v240, v150
	v_add_f32_e32 v241, v241, v151
	v_add_f32_e32 v242, v242, v152
	v_add_f32_e32 v243, v243, v153
	v_add_f32_e32 v244, v244, v154
	v_add_f32_e32 v245, v245, v155
	v_add_f32_e32 v246, v246, v156
	v_add_f32_e32 v247, v247, v157
	v_cvt_pk_bf16_f32 v166, v240, v241
	v_cvt_pk_bf16_f32 v167, v242, v243
	v_cvt_pk_bf16_f32 v168, v244, v245
	v_cvt_pk_bf16_f32 v169, v246, v247
	v_add_u32_e32 v129, 0x48000, v131
	global_store_dwordx4 v129, v[166:169], s[10:11] offset:256
	v_add_u32_e32 v128, 0xb0000, v130
	global_load_dwordx4 v[220:223], v128, s[2:3] offset:256
	v_add_u32_e32 v129, 0x58000, v131
	global_load_dwordx4 v[236:239], v129, s[10:11] offset:256
	s_waitcnt vmcnt(9)
	v_lshlrev_b32_e32 v240, 16, v208
	v_and_b32_e32 v241, 0xffff0000, v208
	v_lshlrev_b32_e32 v242, 16, v209
	v_and_b32_e32 v243, 0xffff0000, v209
	v_lshlrev_b32_e32 v244, 16, v210
	v_and_b32_e32 v245, 0xffff0000, v210
	v_lshlrev_b32_e32 v246, 16, v211
	v_and_b32_e32 v247, 0xffff0000, v211
	v_lshlrev_b32_e32 v150, 16, v224
	v_and_b32_e32 v151, 0xffff0000, v224
	v_lshlrev_b32_e32 v152, 16, v225
	v_and_b32_e32 v153, 0xffff0000, v225
	v_lshlrev_b32_e32 v154, 16, v226
	v_and_b32_e32 v155, 0xffff0000, v226
	v_lshlrev_b32_e32 v156, 16, v227
	v_and_b32_e32 v157, 0xffff0000, v227
	v_mul_f32_e32 v240, v36, v240
	v_mul_f32_e32 v241, v37, v241
	v_mul_f32_e32 v242, v38, v242
	v_mul_f32_e32 v243, v39, v243
	v_mul_f32_e32 v244, v32, v244
	v_mul_f32_e32 v245, v33, v245
	v_mul_f32_e32 v246, v34, v246
	v_mul_f32_e32 v247, v35, v247
	v_add_f32_e32 v240, v240, v150
	v_add_f32_e32 v241, v241, v151
	v_add_f32_e32 v242, v242, v152
	v_add_f32_e32 v243, v243, v153
	v_add_f32_e32 v244, v244, v154
	v_add_f32_e32 v245, v245, v155
	v_add_f32_e32 v246, v246, v156
	v_add_f32_e32 v247, v247, v157
	v_cvt_pk_bf16_f32 v158, v240, v241
	v_cvt_pk_bf16_f32 v159, v242, v243
	v_cvt_pk_bf16_f32 v160, v244, v245
	v_cvt_pk_bf16_f32 v161, v246, v247
	v_add_u32_e32 v129, 0x50000, v131
	global_store_dwordx4 v129, v[158:161], s[10:11]
	s_waitcnt vmcnt(7)
	v_lshlrev_b32_e32 v240, 16, v212
	v_and_b32_e32 v241, 0xffff0000, v212
	v_lshlrev_b32_e32 v242, 16, v213
	v_and_b32_e32 v243, 0xffff0000, v213
	v_lshlrev_b32_e32 v244, 16, v214
	v_and_b32_e32 v245, 0xffff0000, v214
	v_lshlrev_b32_e32 v246, 16, v215
	v_and_b32_e32 v247, 0xffff0000, v215
	v_lshlrev_b32_e32 v150, 16, v228
	v_and_b32_e32 v151, 0xffff0000, v228
	v_lshlrev_b32_e32 v152, 16, v229
	v_and_b32_e32 v153, 0xffff0000, v229
	v_lshlrev_b32_e32 v154, 16, v230
	v_and_b32_e32 v155, 0xffff0000, v230
	v_lshlrev_b32_e32 v156, 16, v231
	v_and_b32_e32 v157, 0xffff0000, v231
	v_mul_f32_e32 v240, v12, v240
	v_mul_f32_e32 v241, v13, v241
	v_mul_f32_e32 v242, v14, v242
	v_mul_f32_e32 v243, v15, v243
	v_mul_f32_e32 v244, v8, v244
	v_mul_f32_e32 v245, v9, v245
	v_mul_f32_e32 v246, v10, v246
	v_mul_f32_e32 v247, v11, v247
	v_add_f32_e32 v240, v240, v150
	v_add_f32_e32 v241, v241, v151
	v_add_f32_e32 v242, v242, v152
	v_add_f32_e32 v243, v243, v153
	v_add_f32_e32 v244, v244, v154
	v_add_f32_e32 v245, v245, v155
	v_add_f32_e32 v246, v246, v156
	v_add_f32_e32 v247, v247, v157
	v_cvt_pk_bf16_f32 v166, v240, v241
	v_cvt_pk_bf16_f32 v167, v242, v243
	v_cvt_pk_bf16_f32 v168, v244, v245
	v_cvt_pk_bf16_f32 v169, v246, v247
	v_add_u32_e32 v129, 0x50000, v131
	global_store_dwordx4 v129, v[166:169], s[10:11] offset:256
	s_waitcnt vmcnt(5)
	v_lshlrev_b32_e32 v240, 16, v216
	v_and_b32_e32 v241, 0xffff0000, v216
	v_lshlrev_b32_e32 v242, 16, v217
	v_and_b32_e32 v243, 0xffff0000, v217
	v_lshlrev_b32_e32 v244, 16, v218
	v_and_b32_e32 v245, 0xffff0000, v218
	v_lshlrev_b32_e32 v246, 16, v219
	v_and_b32_e32 v247, 0xffff0000, v219
	v_lshlrev_b32_e32 v150, 16, v232
	v_and_b32_e32 v151, 0xffff0000, v232
	v_lshlrev_b32_e32 v152, 16, v233
	v_and_b32_e32 v153, 0xffff0000, v233
	v_lshlrev_b32_e32 v154, 16, v234
	v_and_b32_e32 v155, 0xffff0000, v234
	v_lshlrev_b32_e32 v156, 16, v235
	v_and_b32_e32 v157, 0xffff0000, v235
	v_mul_f32_e32 v240, v20, v240
	v_mul_f32_e32 v241, v21, v241
	v_mul_f32_e32 v242, v22, v242
	v_mul_f32_e32 v243, v23, v243
	v_mul_f32_e32 v244, v16, v244
	v_mul_f32_e32 v245, v17, v245
	v_mul_f32_e32 v246, v18, v246
	v_mul_f32_e32 v247, v19, v247
	v_add_f32_e32 v240, v240, v150
	v_add_f32_e32 v241, v241, v151
	v_add_f32_e32 v242, v242, v152
	v_add_f32_e32 v243, v243, v153
	v_add_f32_e32 v244, v244, v154
	v_add_f32_e32 v245, v245, v155
	v_add_f32_e32 v246, v246, v156
	v_add_f32_e32 v247, v247, v157
	v_cvt_pk_bf16_f32 v158, v240, v241
	v_cvt_pk_bf16_f32 v159, v242, v243
	v_cvt_pk_bf16_f32 v160, v244, v245
	v_cvt_pk_bf16_f32 v161, v246, v247
	v_add_u32_e32 v129, 0x58000, v131
	global_store_dwordx4 v129, v[158:161], s[10:11]
	s_waitcnt vmcnt(3)
	v_lshlrev_b32_e32 v240, 16, v220
	v_and_b32_e32 v241, 0xffff0000, v220
	v_lshlrev_b32_e32 v242, 16, v221
	v_and_b32_e32 v243, 0xffff0000, v221
	v_lshlrev_b32_e32 v244, 16, v222
	v_and_b32_e32 v245, 0xffff0000, v222
	v_lshlrev_b32_e32 v246, 16, v223
	v_and_b32_e32 v247, 0xffff0000, v223
	v_lshlrev_b32_e32 v150, 16, v236
	v_and_b32_e32 v151, 0xffff0000, v236
	v_lshlrev_b32_e32 v152, 16, v237
	v_and_b32_e32 v153, 0xffff0000, v237
	v_lshlrev_b32_e32 v154, 16, v238
	v_and_b32_e32 v155, 0xffff0000, v238
	v_lshlrev_b32_e32 v156, 16, v239
	v_and_b32_e32 v157, 0xffff0000, v239
	v_mul_f32_e32 v240, v4, v240
	v_mul_f32_e32 v241, v5, v241
	v_mul_f32_e32 v242, v6, v242
	v_mul_f32_e32 v243, v7, v243
	v_mul_f32_e32 v244, v0, v244
	v_mul_f32_e32 v245, v1, v245
	v_mul_f32_e32 v246, v2, v246
	v_mul_f32_e32 v247, v3, v247
	v_add_f32_e32 v240, v240, v150
	v_add_f32_e32 v241, v241, v151
	v_add_f32_e32 v242, v242, v152
	v_add_f32_e32 v243, v243, v153
	v_add_f32_e32 v244, v244, v154
	v_add_f32_e32 v245, v245, v155
	v_add_f32_e32 v246, v246, v156
	v_add_f32_e32 v247, v247, v157
	v_cvt_pk_bf16_f32 v166, v240, v241
	v_cvt_pk_bf16_f32 v167, v242, v243
	v_cvt_pk_bf16_f32 v168, v244, v245
	v_cvt_pk_bf16_f32 v169, v246, v247
	v_add_u32_e32 v129, 0x58000, v131
	global_store_dwordx4 v129, v[166:169], s[10:11] offset:256
	s_branch .Lproj_done
; DI float bf_lo(unsigned u) { return __uint_as_float(u << 16); }
; DI float bf_hi(unsigned u) { return __uint_as_float(u & 0xffff0000u); }
; #define EPI_ROWS for (int ai = 0; ai < 2; ++ai) for (int m = 0; m < 4; ++m, ({ asm volatile("" ::: "memory"); }))
; DI void store_bf8(bf16_t* p, f32x4 a, f32x4 b) { u32x4 w; w.x = pk2(a[0], a[1]); w.y = pk2(a[2], a[3]); w.z = pk2(b[0], b[1]); w.w = pk2(b[2], b[3]); *(u32x4*)p = w; }
; DI void gemm_run(const GemmDesc& d, char* lds) {
;     ...
;         case E_PROJA: case E_PROJB: {
;             const int goff = d.epi == E_PROJA ? 0 : 1024, c8 = bcol + wc * 32 + fq * 8;
; #pragma unroll
;             EPI_ROWS { const int row = rbase + ai * 128 + m * 16;
; #pragma unroll
;                 for (int bj = 0; bj < 2; ++bj) { const int c = c8 + bj * 128; const u32x4 gw = *(const u32x4*)(P->gates + (long)row * 2048 + goff + c);
;                     f32x4 g0 = {bf_lo(gw.x), bf_hi(gw.x), bf_lo(gw.y), bf_hi(gw.y)}, g1 = {bf_lo(gw.z), bf_hi(gw.z), bf_lo(gw.w), bf_hi(gw.w)};
;                     f32x4 v0 = acc[ai][bj][m][0] * g0, v1 = acc[ai][bj][m][1] * g1;
;                     bf16_t* dst = P->merged + (long)row * 1024 + c;
;                     if (d.epi == E_PROJB) { const u32x4 pw = *(const u32x4*)dst;
;                         v0 += (f32x4){bf_lo(pw.x), bf_hi(pw.x), bf_lo(pw.y), bf_hi(pw.y)}; v1 += (f32x4){bf_lo(pw.z), bf_hi(pw.z), bf_lo(pw.w), bf_hi(pw.w)}; }
;                     store_bf8(dst, v0, v1); } }
.Lproj_a:
	v_mov_b32_e32 v128, v130
	global_load_dwordx4 v[208:211], v128, s[2:3]
	v_mov_b32_e32 v128, v130
	global_load_dwordx4 v[212:215], v128, s[2:3] offset:256
	v_add_u32_e32 v128, 0x10000, v130
	global_load_dwordx4 v[216:219], v128, s[2:3]
	v_add_u32_e32 v128, 0x10000, v130
	global_load_dwordx4 v[220:223], v128, s[2:3] offset:256
	s_waitcnt vmcnt(3)
	v_lshlrev_b32_e32 v240, 16, v208
	v_and_b32_e32 v241, 0xffff0000, v208
	v_lshlrev_b32_e32 v242, 16, v209
	v_and_b32_e32 v243, 0xffff0000, v209
	v_lshlrev_b32_e32 v244, 16, v210
	v_and_b32_e32 v245, 0xffff0000, v210
	v_lshlrev_b32_e32 v246, 16, v211
	v_and_b32_e32 v247, 0xffff0000, v211
	v_mul_f32_e32 v240, v124, v240
	v_mul_f32_e32 v241, v125, v241
	v_mul_f32_e32 v242, v126, v242
	v_mul_f32_e32 v243, v127, v243
	v_mul_f32_e32 v244, v120, v244
	v_mul_f32_e32 v245, v121, v245
	v_mul_f32_e32 v246, v122, v246
	v_mul_f32_e32 v247, v123, v247
	v_cvt_pk_bf16_f32 v158, v240, v241
	v_cvt_pk_bf16_f32 v159, v242, v243
	v_cvt_pk_bf16_f32 v160, v244, v245
	v_cvt_pk_bf16_f32 v161, v246, v247
	v_mov_b32_e32 v129, v131
	global_store_dwordx4 v129, v[158:161], s[10:11]
	v_add_u32_e32 v128, 0x20000, v130
	global_load_dwordx4 v[208:211], v128, s[2:3]
	s_waitcnt vmcnt(4)
	v_lshlrev_b32_e32 v240, 16, v212
	v_and_b32_e32 v241, 0xffff0000, v212
	v_lshlrev_b32_e32 v242, 16, v213
	v_and_b32_e32 v243, 0xffff0000, v213
	v_lshlrev_b32_e32 v244, 16, v214
	v_and_b32_e32 v245, 0xffff0000, v214
	v_lshlrev_b32_e32 v246, 16, v215
	v_and_b32_e32 v247, 0xffff0000, v215
	v_mul_f32_e32 v240, v108, v240
	v_mul_f32_e32 v241, v109, v241
	v_mul_f32_e32 v242, v110, v242
	v_mul_f32_e32 v243, v111, v243
	v_mul_f32_e32 v244, v104, v244
	v_mul_f32_e32 v245, v105, v245
	v_mul_f32_e32 v246, v106, v246
	v_mul_f32_e32 v247, v107, v247
	v_cvt_pk_bf16_f32 v166, v240, v241
	v_cvt_pk_bf16_f32 v167, v242, v243
	v_cvt_pk_bf16_f32 v168, v244, v245
	v_cvt_pk_bf16_f32 v169, v246, v247
	v_mov_b32_e32 v129, v131
	global_store_dwordx4 v129, v[166:169], s[10:11] offset:256
	v_add_u32_e32 v128, 0x20000, v130
	global_load_dwordx4 v[212:215], v128, s[2:3] offset:256
	s_waitcnt vmcnt(5)
	v_lshlrev_b32_e32 v240, 16, v216
	v_and_b32_e32 v241, 0xffff0000, v216
	v_lshlrev_b32_e32 v242, 16, v217
	v_and_b32_e32 v243, 0xffff0000, v217
	v_lshlrev_b32_e32 v244, 16, v218
	v_and_b32_e32 v245, 0xffff0000, v218
	v_lshlrev_b32_e32 v246, 16, v219
	v_and_b32_e32 v247, 0xffff0000, v219
	v_mul_f32_e32 v240, v116, v240
	v_mul_f32_e32 v241, v117, v241
	v_mul_f32_e32 v242, v118, v242
	v_mul_f32_e32 v243, v119, v243
	v_mul_f32_e32 v244, v112, v244
	v_mul_f32_e32 v245, v113, v245
	v_mul_f32_e32 v246, v114, v246
	v_mul_f32_e32 v247, v115, v247
	v_cvt_pk_bf16_f32 v158, v240, v241
	v_cvt_pk_bf16_f32 v159, v242, v243
	v_cvt_pk_bf16_f32 v160, v244, v245
	v_cvt_pk_bf16_f32 v161, v246, v247
	v_add_u32_e32 v129, 0x8000, v131
	global_store_dwordx4 v129, v[158:161], s[10:11]
	v_add_u32_e32 v128, 0x30000, v130
	global_load_dwordx4 v[216:219], v128, s[2:3]
	s_waitcnt vmcnt(6)
	v_lshlrev_b32_e32 v240, 16, v220
	v_and_b32_e32 v241, 0xffff0000, v220
	v_lshlrev_b32_e32 v242, 16, v221
	v_and_b32_e32 v243, 0xffff0000, v221
	v_lshlrev_b32_e32 v244, 16, v222
	v_and_b32_e32 v245, 0xffff0000, v222
	v_lshlrev_b32_e32 v246, 16, v223
	v_and_b32_e32 v247, 0xffff0000, v223
	v_mul_f32_e32 v240, v92, v240
	v_mul_f32_e32 v241, v93, v241
	v_mul_f32_e32 v242, v94, v242
	v_mul_f32_e32 v243, v95, v243
	v_mul_f32_e32 v244, v88, v244
	v_mul_f32_e32 v245, v89, v245
	v_mul_f32_e32 v246, v90, v246
	v_mul_f32_e32 v247, v91, v247
	v_cvt_pk_bf16_f32 v166, v240, v241
	v_cvt_pk_bf16_f32 v167, v242, v243
	v_cvt_pk_bf16_f32 v168, v244, v245
	v_cvt_pk_bf16_f32 v169, v246, v247
	v_add_u32_e32 v129, 0x8000, v131
	global_store_dwordx4 v129, v[166:169], s[10:11] offset:256
	v_add_u32_e32 v128, 0x30000, v130
	global_load_dwordx4 v[220:223], v128, s[2:3] offset:256
	s_waitcnt vmcnt(6)
	v_lshlrev_b32_e32 v240, 16, v208
	v_and_b32_e32 v241, 0xffff0000, v208
	v_lshlrev_b32_e32 v242, 16, v209
	v_and_b32_e32 v243, 0xffff0000, v209
	v_lshlrev_b32_e32 v244, 16, v210
	v_and_b32_e32 v245, 0xffff0000, v210
	v_lshlrev_b32_e32 v246, 16, v211
	v_and_b32_e32 v247, 0xffff0000, v211
	v_mul_f32_e32 v240, v100, v240
	v_mul_f32_e32 v241, v101, v241
	v_mul_f32_e32 v242, v102, v242
	v_mul_f32_e32 v243, v103, v243
	v_mul_f32_e32 v244, v96, v244
	v_mul_f32_e32 v245, v97, v245
	v_mul_f32_e32 v246, v98, v246
	v_mul_f32_e32 v247, v99, v247
	v_cvt_pk_bf16_f32 v158, v240, v241
	v_cvt_pk_bf16_f32 v159, v242, v243
	v_cvt_pk_bf16_f32 v160, v244, v245
	v_cvt_pk_bf16_f32 v161, v246, v247
	v_add_u32_e32 v129, 0x10000, v131
	global_store_dwordx4 v129, v[158:161], s[10:11]
	v_add_u32_e32 v128, 0x80000, v130
	global_load_dwordx4 v[208:211], v128, s[2:3]
	s_waitcnt vmcnt(6)
	v_lshlrev_b32_e32 v240, 16, v212
	v_and_b32_e32 v241, 0xffff0000, v212
	v_lshlrev_b32_e32 v242, 16, v213
	v_and_b32_e32 v243, 0xffff0000, v213
	v_lshlrev_b32_e32 v244, 16, v214
	v_and_b32_e32 v245, 0xffff0000, v214
	v_lshlrev_b32_e32 v246, 16, v215
	v_and_b32_e32 v247, 0xffff0000, v215
	v_mul_f32_e32 v240, v76, v240
	v_mul_f32_e32 v241, v77, v241
	v_mul_f32_e32 v242, v78, v242
	v_mul_f32_e32 v243, v79, v243
	v_mul_f32_e32 v244, v72, v244
	v_mul_f32_e32 v245, v73, v245
	v_mul_f32_e32 v246, v74, v246
	v_mul_f32_e32 v247, v75, v247
	v_cvt_pk_bf16_f32 v166, v240, v241
	v_cvt_pk_bf16_f32 v167, v242, v243
	v_cvt_pk_bf16_f32 v168, v244, v245
	v_cvt_pk_bf16_f32 v169, v246, v247
	v_add_u32_e32 v129, 0x10000, v131
	global_store_dwordx4 v129, v[166:169], s[10:11] offset:256
	v_add_u32_e32 v128, 0x80000, v130
	global_load_dwordx4 v[212:215], v128, s[2:3] offset:256
	s_waitcnt vmcnt(6)
; DI float bf_lo(unsigned u) { return __uint_as_float(u << 16); }
; DI float bf_hi(unsigned u) { return __uint_as_float(u & 0xffff0000u); }
; #define EPI_ROWS for (int ai = 0; ai < 2; ++ai) for (int m = 0; m < 4; ++m, ({ asm volatile("" ::: "memory"); }))
; DI void store_bf8(bf16_t* p, f32x4 a, f32x4 b) { u32x4 w; w.x = pk2(a[0], a[1]); w.y = pk2(a[2], a[3]); w.z = pk2(b[0], b[1]); w.w = pk2(b[2], b[3]); *(u32x4*)p = w; }
; DI void gemm_run(const GemmDesc& d, char* lds) {
;     ...
;         case E_PROJA: case E_PROJB: {
;             const int goff = d.epi == E_PROJA ? 0 : 1024, c8 = bcol + wc * 32 + fq * 8;
; #pragma unroll
;             EPI_ROWS { const int row = rbase + ai * 128 + m * 16;
; #pragma unroll
;                 for (int bj = 0; bj < 2; ++bj) { const int c = c8 + bj * 128; const u32x4 gw = *(const u32x4*)(P->gates + (long)row * 2048 + goff + c);
;                     f32x4 g0 = {bf_lo(gw.x), bf_hi(gw.x), bf_lo(gw.y), bf_hi(gw.y)}, g1 = {bf_lo(gw.z), bf_hi(gw.z), bf_lo(gw.w), bf_hi(gw.w)};
;                     f32x4 v0 = acc[ai][bj][m][0] * g0, v1 = acc[ai][bj][m][1] * g1;
;                     bf16_t* dst = P->merged + (long)row * 1024 + c;
;                     if (d.epi == E_PROJB) { const u32x4 pw = *(const u32x4*)dst;
;                         v0 += (f32x4){bf_lo(pw.x), bf_hi(pw.x), bf_lo(pw.y), bf_hi(pw.y)}; v1 += (f32x4){bf_lo(pw.z), bf_hi(pw.z), bf_lo(pw.w), bf_hi(pw.w)}; }
;                     store_bf8(dst, v0, v1); } }
	v_lshlrev_b32_e32 v240, 16, v216
	v_and_b32_e32 v241, 0xffff0000, v216
	v_lshlrev_b32_e32 v242, 16, v217
	v_and_b32_e32 v243, 0xffff0000, v217
	v_lshlrev_b32_e32 v244, 16, v218
	v_and_b32_e32 v245, 0xffff0000, v218
	v_lshlrev_b32_e32 v246, 16, v219
	v_and_b32_e32 v247, 0xffff0000, v219
	v_mul_f32_e32 v240, v84, v240
	v_mul_f32_e32 v241, v85, v241
	v_mul_f32_e32 v242, v86, v242
	v_mul_f32_e32 v243, v87, v243
	v_mul_f32_e32 v244, v80, v244
	v_mul_f32_e32 v245, v81, v245
	v_mul_f32_e32 v246, v82, v246
	v_mul_f32_e32 v247, v83, v247
	v_cvt_pk_bf16_f32 v158, v240, v241
	v_cvt_pk_bf16_f32 v159, v242, v243
	v_cvt_pk_bf16_f32 v160, v244, v245
	v_cvt_pk_bf16_f32 v161, v246, v247
	v_add_u32_e32 v129, 0x18000, v131
	global_store_dwordx4 v129, v[158:161], s[10:11]
	v_add_u32_e32 v128, 0x90000, v130
	global_load_dwordx4 v[216:219], v128, s[2:3]
	s_waitcnt vmcnt(6)
	v_lshlrev_b32_e32 v240, 16, v220
	v_and_b32_e32 v241, 0xffff0000, v220
	v_lshlrev_b32_e32 v242, 16, v221
	v_and_b32_e32 v243, 0xffff0000, v221
	v_lshlrev_b32_e32 v244, 16, v222
	v_and_b32_e32 v245, 0xffff0000, v222
	v_lshlrev_b32_e32 v246, 16, v223
	v_and_b32_e32 v247, 0xffff0000, v223
	v_mul_f32_e32 v240, v68, v240
	v_mul_f32_e32 v241, v69, v241
	v_mul_f32_e32 v242, v70, v242
	v_mul_f32_e32 v243, v71, v243
	v_mul_f32_e32 v244, v64, v244
	v_mul_f32_e32 v245, v65, v245
	v_mul_f32_e32 v246, v66, v246
	v_mul_f32_e32 v247, v67, v247
	v_cvt_pk_bf16_f32 v166, v240, v241
	v_cvt_pk_bf16_f32 v167, v242, v243
	v_cvt_pk_bf16_f32 v168, v244, v245
	v_cvt_pk_bf16_f32 v169, v246, v247
	v_add_u32_e32 v129, 0x18000, v131
	global_store_dwordx4 v129, v[166:169], s[10:11] offset:256
	v_add_u32_e32 v128, 0x90000, v130
	global_load_dwordx4 v[220:223], v128, s[2:3] offset:256
	s_waitcnt vmcnt(6)
	v_lshlrev_b32_e32 v240, 16, v208
	v_and_b32_e32 v241, 0xffff0000, v208
	v_lshlrev_b32_e32 v242, 16, v209
	v_and_b32_e32 v243, 0xffff0000, v209
	v_lshlrev_b32_e32 v244, 16, v210
	v_and_b32_e32 v245, 0xffff0000, v210
	v_lshlrev_b32_e32 v246, 16, v211
	v_and_b32_e32 v247, 0xffff0000, v211
	v_mul_f32_e32 v240, v60, v240
	v_mul_f32_e32 v241, v61, v241
	v_mul_f32_e32 v242, v62, v242
	v_mul_f32_e32 v243, v63, v243
	v_mul_f32_e32 v244, v56, v244
	v_mul_f32_e32 v245, v57, v245
	v_mul_f32_e32 v246, v58, v246
	v_mul_f32_e32 v247, v59, v247
	v_cvt_pk_bf16_f32 v158, v240, v241
	v_cvt_pk_bf16_f32 v159, v242, v243
	v_cvt_pk_bf16_f32 v160, v244, v245
	v_cvt_pk_bf16_f32 v161, v246, v247
	v_add_u32_e32 v129, 0x40000, v131
	global_store_dwordx4 v129, v[158:161], s[10:11]
	v_add_u32_e32 v128, 0xa0000, v130
	global_load_dwordx4 v[208:211], v128, s[2:3]
	s_waitcnt vmcnt(6)
	v_lshlrev_b32_e32 v240, 16, v212
	v_and_b32_e32 v241, 0xffff0000, v212
	v_lshlrev_b32_e32 v242, 16, v213
	v_and_b32_e32 v243, 0xffff0000, v213
	v_lshlrev_b32_e32 v244, 16, v214
	v_and_b32_e32 v245, 0xffff0000, v214
	v_lshlrev_b32_e32 v246, 16, v215
	v_and_b32_e32 v247, 0xffff0000, v215
	v_mul_f32_e32 v240, v44, v240
	v_mul_f32_e32 v241, v45, v241
	v_mul_f32_e32 v242, v46, v242
	v_mul_f32_e32 v243, v47, v243
	v_mul_f32_e32 v244, v40, v244
	v_mul_f32_e32 v245, v41, v245
	v_mul_f32_e32 v246, v42, v246
	v_mul_f32_e32 v247, v43, v247
	v_cvt_pk_bf16_f32 v166, v240, v241
	v_cvt_pk_bf16_f32 v167, v242, v243
	v_cvt_pk_bf16_f32 v168, v244, v245
	v_cvt_pk_bf16_f32 v169, v246, v247
	v_add_u32_e32 v129, 0x40000, v131
	global_store_dwordx4 v129, v[166:169], s[10:11] offset:256
	v_add_u32_e32 v128, 0xa0000, v130
	global_load_dwordx4 v[212:215], v128, s[2:3] offset:256
	s_waitcnt vmcnt(6)
	v_lshlrev_b32_e32 v240, 16, v216
	v_and_b32_e32 v241, 0xffff0000, v216
	v_lshlrev_b32_e32 v242, 16, v217
	v_and_b32_e32 v243, 0xffff0000, v217
	v_lshlrev_b32_e32 v244, 16, v218
	v_and_b32_e32 v245, 0xffff0000, v218
	v_lshlrev_b32_e32 v246, 16, v219
	v_and_b32_e32 v247, 0xffff0000, v219
	v_mul_f32_e32 v240, v52, v240
	v_mul_f32_e32 v241, v53, v241
	v_mul_f32_e32 v242, v54, v242
	v_mul_f32_e32 v243, v55, v243
	v_mul_f32_e32 v244, v48, v244
	v_mul_f32_e32 v245, v49, v245
	v_mul_f32_e32 v246, v50, v246
	v_mul_f32_e32 v247, v51, v247
	v_cvt_pk_bf16_f32 v158, v240, v241
	v_cvt_pk_bf16_f32 v159, v242, v243
	v_cvt_pk_bf16_f32 v160, v244, v245
	v_cvt_pk_bf16_f32 v161, v246, v247
	v_add_u32_e32 v129, 0x48000, v131
	global_store_dwordx4 v129, v[158:161], s[10:11]
	v_add_u32_e32 v128, 0xb0000, v130
	global_load_dwordx4 v[216:219], v128, s[2:3]
	s_waitcnt vmcnt(6)
; DI float bf_lo(unsigned u) { return __uint_as_float(u << 16); }
; DI float bf_hi(unsigned u) { return __uint_as_float(u & 0xffff0000u); }
; #define EPI_ROWS for (int ai = 0; ai < 2; ++ai) for (int m = 0; m < 4; ++m, ({ asm volatile("" ::: "memory"); }))
; DI void store_bf8(bf16_t* p, f32x4 a, f32x4 b) { u32x4 w; w.x = pk2(a[0], a[1]); w.y = pk2(a[2], a[3]); w.z = pk2(b[0], b[1]); w.w = pk2(b[2], b[3]); *(u32x4*)p = w; }
; DI void gemm_run(const GemmDesc& d, char* lds) {
;     ...
;         case E_PROJA: case E_PROJB: {
;             const int goff = d.epi == E_PROJA ? 0 : 1024, c8 = bcol + wc * 32 + fq * 8;
; #pragma unroll
;             EPI_ROWS { const int row = rbase + ai * 128 + m * 16;
; #pragma unroll
;                 for (int bj = 0; bj < 2; ++bj) { const int c = c8 + bj * 128; const u32x4 gw = *(const u32x4*)(P->gates + (long)row * 2048 + goff + c);
;                     f32x4 g0 = {bf_lo(gw.x), bf_hi(gw.x), bf_lo(gw.y), bf_hi(gw.y)}, g1 = {bf_lo(gw.z), bf_hi(gw.z), bf_lo(gw.w), bf_hi(gw.w)};
;                     f32x4 v0 = acc[ai][bj][m][0] * g0, v1 = acc[ai][bj][m][1] * g1;
;                     bf16_t* dst = P->merged + (long)row * 1024 + c;
;                     if (d.epi == E_PROJB) { const u32x4 pw = *(const u32x4*)dst;
;                         v0 += (f32x4){bf_lo(pw.x), bf_hi(pw.x), bf_lo(pw.y), bf_hi(pw.y)}; v1 += (f32x4){bf_lo(pw.z), bf_hi(pw.z), bf_lo(pw.w), bf_hi(pw.w)}; }
;                     store_bf8(dst, v0, v1); } }
	v_lshlrev_b32_e32 v240, 16, v220
	v_and_b32_e32 v241, 0xffff0000, v220
	v_lshlrev_b32_e32 v242, 16, v221
	v_and_b32_e32 v243, 0xffff0000, v221
	v_lshlrev_b32_e32 v244, 16, v222
	v_and_b32_e32 v245, 0xffff0000, v222
	v_lshlrev_b32_e32 v246, 16, v223
	v_and_b32_e32 v247, 0xffff0000, v223
	v_mul_f32_e32 v240, v28, v240
	v_mul_f32_e32 v241, v29, v241
	v_mul_f32_e32 v242, v30, v242
	v_mul_f32_e32 v243, v31, v243
	v_mul_f32_e32 v244, v24, v244
	v_mul_f32_e32 v245, v25, v245
	v_mul_f32_e32 v246, v26, v246
	v_mul_f32_e32 v247, v27, v247
	v_cvt_pk_bf16_f32 v166, v240, v241
	v_cvt_pk_bf16_f32 v167, v242, v243
	v_cvt_pk_bf16_f32 v168, v244, v245
	v_cvt_pk_bf16_f32 v169, v246, v247
	v_add_u32_e32 v129, 0x48000, v131
	global_store_dwordx4 v129, v[166:169], s[10:11] offset:256
	v_add_u32_e32 v128, 0xb0000, v130
	global_load_dwordx4 v[220:223], v128, s[2:3] offset:256
	s_waitcnt vmcnt(6)
	v_lshlrev_b32_e32 v240, 16, v208
	v_and_b32_e32 v241, 0xffff0000, v208
	v_lshlrev_b32_e32 v242, 16, v209
	v_and_b32_e32 v243, 0xffff0000, v209
	v_lshlrev_b32_e32 v244, 16, v210
	v_and_b32_e32 v245, 0xffff0000, v210
	v_lshlrev_b32_e32 v246, 16, v211
	v_and_b32_e32 v247, 0xffff0000, v211
	v_mul_f32_e32 v240, v36, v240
	v_mul_f32_e32 v241, v37, v241
	v_mul_f32_e32 v242, v38, v242
	v_mul_f32_e32 v243, v39, v243
	v_mul_f32_e32 v244, v32, v244
	v_mul_f32_e32 v245, v33, v245
	v_mul_f32_e32 v246, v34, v246
	v_mul_f32_e32 v247, v35, v247
	v_cvt_pk_bf16_f32 v158, v240, v241
	v_cvt_pk_bf16_f32 v159, v242, v243
	v_cvt_pk_bf16_f32 v160, v244, v245
	v_cvt_pk_bf16_f32 v161, v246, v247
	v_add_u32_e32 v129, 0x50000, v131
	global_store_dwordx4 v129, v[158:161], s[10:11]
	s_waitcnt vmcnt(5)
	v_lshlrev_b32_e32 v240, 16, v212
	v_and_b32_e32 v241, 0xffff0000, v212
	v_lshlrev_b32_e32 v242, 16, v213
	v_and_b32_e32 v243, 0xffff0000, v213
	v_lshlrev_b32_e32 v244, 16, v214
	v_and_b32_e32 v245, 0xffff0000, v214
	v_lshlrev_b32_e32 v246, 16, v215
	v_and_b32_e32 v247, 0xffff0000, v215
	v_mul_f32_e32 v240, v12, v240
	v_mul_f32_e32 v241, v13, v241
	v_mul_f32_e32 v242, v14, v242
	v_mul_f32_e32 v243, v15, v243
	v_mul_f32_e32 v244, v8, v244
	v_mul_f32_e32 v245, v9, v245
	v_mul_f32_e32 v246, v10, v246
	v_mul_f32_e32 v247, v11, v247
	v_cvt_pk_bf16_f32 v166, v240, v241
	v_cvt_pk_bf16_f32 v167, v242, v243
	v_cvt_pk_bf16_f32 v168, v244, v245
	v_cvt_pk_bf16_f32 v169, v246, v247
	v_add_u32_e32 v129, 0x50000, v131
	global_store_dwordx4 v129, v[166:169], s[10:11] offset:256
	s_waitcnt vmcnt(4)
	v_lshlrev_b32_e32 v240, 16, v216
	v_and_b32_e32 v241, 0xffff0000, v216
	v_lshlrev_b32_e32 v242, 16, v217
	v_and_b32_e32 v243, 0xffff0000, v217
	v_lshlrev_b32_e32 v244, 16, v218
	v_and_b32_e32 v245, 0xffff0000, v218
	v_lshlrev_b32_e32 v246, 16, v219
	v_and_b32_e32 v247, 0xffff0000, v219
	v_mul_f32_e32 v240, v20, v240
	v_mul_f32_e32 v241, v21, v241
	v_mul_f32_e32 v242, v22, v242
	v_mul_f32_e32 v243, v23, v243
	v_mul_f32_e32 v244, v16, v244
	v_mul_f32_e32 v245, v17, v245
	v_mul_f32_e32 v246, v18, v246
	v_mul_f32_e32 v247, v19, v247
	v_cvt_pk_bf16_f32 v158, v240, v241
	v_cvt_pk_bf16_f32 v159, v242, v243
	v_cvt_pk_bf16_f32 v160, v244, v245
	v_cvt_pk_bf16_f32 v161, v246, v247
	v_add_u32_e32 v129, 0x58000, v131
	global_store_dwordx4 v129, v[158:161], s[10:11]
	s_waitcnt vmcnt(3)
	v_lshlrev_b32_e32 v240, 16, v220
	v_and_b32_e32 v241, 0xffff0000, v220
	v_lshlrev_b32_e32 v242, 16, v221
	v_and_b32_e32 v243, 0xffff0000, v221
	v_lshlrev_b32_e32 v244, 16, v222
	v_and_b32_e32 v245, 0xffff0000, v222
	v_lshlrev_b32_e32 v246, 16, v223
	v_and_b32_e32 v247, 0xffff0000, v223
	v_mul_f32_e32 v240, v4, v240
	v_mul_f32_e32 v241, v5, v241
	v_mul_f32_e32 v242, v6, v242
	v_mul_f32_e32 v243, v7, v243
	v_mul_f32_e32 v244, v0, v244
	v_mul_f32_e32 v245, v1, v245
	v_mul_f32_e32 v246, v2, v246
	v_mul_f32_e32 v247, v3, v247
	v_cvt_pk_bf16_f32 v166, v240, v241
	v_cvt_pk_bf16_f32 v167, v242, v243
	v_cvt_pk_bf16_f32 v168, v244, v245
	v_cvt_pk_bf16_f32 v169, v246, v247
	v_add_u32_e32 v129, 0x58000, v131
	global_store_dwordx4 v129, v[166:169], s[10:11] offset:256
